# rebalanced weight-conversion pocket ranges (in-proj/MLP1 pockets shrunk, branch pocket grown) on top of gate epilogue + LN fixes
# speedup vs baseline: 1.0073x; 1.0018x over previous
; __device__ __forceinline__ void convert_pocket(Frame& F, int lnext, int r_lo, int r_hi, int first_idle) {
;     const int c = (int)blockIdx.x; if (lnext >= DEPTH || c < first_idle) return;
;     convert_items(F, lnext, r_lo, r_hi, (c - first_idle) * NWAVES + F.wave, ((int)gridDim.x - first_idle) * NWAVES);
; }
.LBB0_297:
	s_ashr_i32 s15, s54, 1
	s_lshr_b32 s2, s15, 30
	s_add_i32 s14, s15, s2
	s_ashr_i32 s13, s14, 2
	s_lshl_b32 s10, s47, 2
	s_bfe_u32 s16, s33, 0x10008
	s_and_b32 s12, s13, 1
	s_cmpk_lt_i32 s47, 0x80
	s_cselect_b64 s[2:3], -1, 0
	s_and_b64 s[2:3], s[2:3], exec
	s_cselect_b32 s5, -5, 0xffffff7c
	s_cmp_eq_u32 s12, 0
	s_cselect_b64 s[36:37], -1, 0
	s_and_b64 s[2:3], s[36:37], exec
	s_cselect_b32 s11, 3, 0
	s_cselect_b32 s4, 31, 0
	s_cmp_eq_u32 s16, 0
	s_cselect_b64 s[78:79], -1, 0
	s_and_b64 s[2:3], s[78:79], exec
	s_cselect_b32 s17, 3, 0
	s_cselect_b32 s6, 31, 0
	s_cmpk_lt_i32 s47, 0x80
	s_cselect_b64 s[2:3], -1, 0
	s_mul_i32 s7, s47, 3
	s_and_b64 s[8:9], s[2:3], exec
	s_cselect_b32 s7, s7, s10
	s_lshl_b32 s8, s81, 3
	s_add_i32 s9, s46, s8
	s_add_u32 s38, s70, 0x2c000000
	s_addc_u32 s39, s71, 0
	s_add_u32 s8, s70, 0x1300000
	v_writelane_b32 v248, s8, 11
	s_addc_u32 s8, s71, 0
	s_add_u32 s84, s70, 0x2e400000
	s_addc_u32 s85, s71, 0
	s_cmpk_lt_i32 s81, 0x9b4
	s_cselect_b64 s[18:19], -1, 0
	s_ashr_i32 s31, s81, 31
	v_writelane_b32 v248, s8, 12
	s_lshr_b32 s8, s31, 29
	s_load_dword s30, s[82:83], 0xc8
	s_add_i32 s8, s81, s8
	s_ashr_i32 s35, s8, 3
	s_and_b32 s8, s8, -8
	s_sub_i32 s40, s81, s8
	v_writelane_b32 v248, s18, 13
	s_mul_i32 s8, s40, 0x136
	s_add_i32 s8, s8, 4
	v_writelane_b32 v248, s19, 14
	s_waitcnt lgkmcnt(0)
	s_ashr_i32 s18, s30, 31
	s_cmpk_eq_i32 s30, 0x100
	v_writelane_b32 v248, s18, 15
	s_cselect_b64 s[18:19], -1, 0
	v_writelane_b32 v248, s18, 16
	s_cmpk_lt_i32 s81, 0xb4
	s_mov_b32 s34, s54
	v_writelane_b32 v248, s19, 17
	s_cselect_b64 s[18:19], -1, 0
	v_writelane_b32 v248, s18, 18
	s_mov_b32 s77, 0
	s_mul_i32 s55, s16, 0x90
	v_writelane_b32 v248, s19, 19
	s_add_i32 s18, s9, 0x2600
	s_cmpk_lt_i32 s18, 0x41e4
	v_writelane_b32 v248, s18, 20
	s_cselect_b64 s[18:19], -1, 0
	v_writelane_b32 v248, s18, 21
	v_mov_b32_e32 v0, 0x90
	v_mul_u32_u24_e32 v0, s12, v0
	v_writelane_b32 v248, s19, 22
	s_add_i32 s19, s50, 0
	s_add_u32 s18, s70, 0x12800000
	v_writelane_b32 v248, s18, 23
	s_addc_u32 s18, s71, 0
	s_cmp_eq_u32 s49, 0
	v_writelane_b32 v248, s18, 24
	s_cselect_b64 s[20:21], -1, 0
	v_writelane_b32 v248, s20, 25
	v_readfirstlane_b32 s62, v0
	s_mov_b32 s61, s77
	v_writelane_b32 v248, s21, 26
	s_add_u32 s20, s70, 0x4200
	s_addc_u32 s21, s71, 0
	v_writelane_b32 v248, s20, 27
	s_mov_b32 s65, s77
	v_mov_b32_e32 v65, 0
	v_writelane_b32 v248, s21, 28
	s_add_u32 s20, s70, 0x4400
	s_addc_u32 s21, s71, 0
	v_writelane_b32 v248, s20, 29
	v_mov_b32_e32 v199, 1
	v_mov_b32_e32 v200, 0xbadba0
	v_writelane_b32 v248, s21, 30
	s_add_u32 s20, s70, 0x4500
	s_addc_u32 s21, s71, 0
	v_writelane_b32 v248, s20, 31
	v_mov_b32_e32 v202, 0x358637bd
	v_mov_b32_e32 v203, 0x260
	v_writelane_b32 v248, s21, 32
	s_add_u32 s20, s70, 0x4600
	s_addc_u32 s21, s71, 0
	v_writelane_b32 v248, s20, 33
	v_mov_b32_e32 v204, 0x3727c5ac
	v_mov_b64_e32 v[162:163], 0x9b4
	v_writelane_b32 v248, s21, 34
	s_add_u32 s20, s70, 0x4700
	s_addc_u32 s21, s71, 0
	v_writelane_b32 v248, s20, 35
	v_mov_b64_e32 v[164:165], 0x9b3
	v_mov_b32_e32 v205, 0x228000
	v_writelane_b32 v248, s21, 36
	s_add_u32 s20, s70, 0x4800
	s_addc_u32 s21, s71, 0
	v_writelane_b32 v248, s20, 37
	v_mov_b32_e32 v206, 0xf149f2ca
	v_mov_b64_e32 v[166:167], 0x100
	v_writelane_b32 v248, s21, 38
	s_add_u32 s20, s70, 0x4900
	s_addc_u32 s21, s71, 0
	v_writelane_b32 v248, s20, 39
	v_mov_b64_e32 v[168:169], 0xff
	v_mov_b64_e32 v[170:171], 0x60
	v_writelane_b32 v248, s21, 40
	s_add_u32 s20, s70, 0x4a00
	s_addc_u32 s21, s71, 0
	v_writelane_b32 v248, s20, 41
	v_mov_b64_e32 v[172:173], 0x5f
	v_mov_b64_e32 v[174:175], 0xc0
	v_writelane_b32 v248, s21, 42
	s_add_u32 s20, s70, 0x4b00
	s_addc_u32 s21, s71, 0
	v_writelane_b32 v248, s20, 43
	v_mov_b64_e32 v[176:177], 0xbf
	v_mov_b32_e32 v207, 0xc000
	v_writelane_b32 v248, s21, 44
	s_add_u32 s20, s70, 0x4c00
	s_addc_u32 s21, s71, 0
	v_writelane_b32 v248, s20, 45
	s_movk_i32 s88, 0x4000
	s_mov_b32 s89, 0x8000
	v_writelane_b32 v248, s21, 46
	s_add_u32 s20, s70, 0x4d00
	s_addc_u32 s21, s71, 0
	v_writelane_b32 v248, s20, 47
	s_mov_b32 s66, 0xffff0000
	s_mov_b32 s90, 0xc000
	v_writelane_b32 v248, s21, 48
	s_add_u32 s20, s70, 0x4e00
	s_addc_u32 s21, s71, 0
	v_writelane_b32 v248, s20, 49
	s_mov_b32 s91, 0x8a00
	s_movk_i32 s67, 0x1000
	v_writelane_b32 v248, s21, 50
	s_add_u32 s20, s70, 0x4f00
	s_addc_u32 s21, s71, 0
	v_writelane_b32 v248, s20, 51
	s_mov_b32 s93, 0xf800000
	s_nop 0
	v_writelane_b32 v248, s21, 52
	s_add_u32 s20, s70, 0x5000
	s_addc_u32 s21, s71, 0
	v_writelane_b32 v248, s20, 53
	s_nop 1
	v_writelane_b32 v248, s21, 54
	s_add_u32 s20, s70, 0x5100
	s_addc_u32 s21, s71, 0
	v_writelane_b32 v248, s20, 55
	s_nop 1
	v_writelane_b32 v248, s21, 56
	s_add_u32 s20, s70, 0x5200
	s_addc_u32 s21, s71, 0
	v_writelane_b32 v248, s20, 57
	s_nop 1
	v_writelane_b32 v248, s21, 58
	s_add_u32 s20, s70, 0x5300
	s_addc_u32 s21, s71, 0
	v_writelane_b32 v248, s20, 59
	s_cmp_eq_u32 s48, 15
	s_nop 0
	v_writelane_b32 v248, s21, 60
	s_cselect_b64 s[20:21], -1, 0
	v_writelane_b32 v248, s20, 61
	s_cmp_eq_u32 s48, 14
	s_nop 0
	v_writelane_b32 v248, s21, 62
	s_cselect_b64 s[20:21], -1, 0
	v_writelane_b32 v248, s20, 63
	s_cmp_eq_u32 s48, 13
	s_nop 0
	v_writelane_b32 v249, s21, 0
	s_cselect_b64 s[20:21], -1, 0
	v_writelane_b32 v249, s20, 1
	s_cmp_eq_u32 s48, 12
	s_nop 0
	v_writelane_b32 v249, s21, 2
	s_cselect_b64 s[20:21], -1, 0
	v_writelane_b32 v249, s20, 3
	s_cmp_eq_u32 s48, 11
	s_nop 0
	v_writelane_b32 v249, s21, 4
	s_cselect_b64 s[20:21], -1, 0
	v_writelane_b32 v249, s20, 5
	s_cmp_eq_u32 s48, 10
	s_nop 0
	v_writelane_b32 v249, s21, 6
	s_cselect_b64 s[20:21], -1, 0
	v_writelane_b32 v249, s20, 7
	s_cmp_eq_u32 s48, 9
; __device__ __forceinline__ unsigned xb_ld(unsigned* p)              { return __hip_atomic_load(p, __ATOMIC_RELAXED, __HIP_MEMORY_SCOPE_AGENT); }
; __device__ __forceinline__ void xcd_barrier_complete(unsigned* bar, unsigned x, unsigned& nloc, unsigned& nx) {
;     ...
;         for (unsigned j = 0; j < 16; ++j) { const unsigned c = xb_ld(&bar[XB_XCNT(j)]); sum += c; cnt += (c > 0u) ? 1u : 0u; mine = (j == x) ? c : mine; }
; __device__ __forceinline__ void mixer_phase1(Frame& FF, int l) {
;     ...
;     const bool deal = (F.G == 256); if (deal) { const int w = F.wave, cu = F.vcu;
;         if (w < 4) u0 = w * 256 + cu;
;         else if (w == 4 && cu < 128) u0 = 1024 + cu;
;         else { const int li = cu < 128 ? cu * 3 + (w - 5) : 384 + (cu - 128) * 4 + (w - 4); if (U_F + U_K + li < U_ALL) u0 = U_F + U_K + li; }
;     }
;     const int ustep = deal ? 1 : NGW; const int uend = deal ? 1 : U_ALL;
	s_nop 0
	v_writelane_b32 v249, s21, 8
	s_cselect_b64 s[20:21], -1, 0
	v_writelane_b32 v249, s20, 9
	s_cmp_eq_u32 s48, 8
	s_nop 0
	v_writelane_b32 v249, s21, 10
	s_cselect_b64 s[20:21], -1, 0
	v_writelane_b32 v249, s20, 11
	s_cmp_eq_u32 s48, 7
	s_nop 0
	v_writelane_b32 v249, s21, 12
	s_cselect_b64 s[20:21], -1, 0
	v_writelane_b32 v249, s20, 13
	s_cmp_eq_u32 s48, 6
	s_nop 0
	v_writelane_b32 v249, s21, 14
	s_cselect_b64 s[20:21], -1, 0
	v_writelane_b32 v249, s20, 15
	s_cmp_eq_u32 s48, 5
	s_nop 0
	v_writelane_b32 v249, s21, 16
	s_cselect_b64 s[20:21], -1, 0
	v_writelane_b32 v249, s20, 17
	s_cmp_eq_u32 s48, 4
	s_nop 0
	v_writelane_b32 v249, s21, 18
	s_cselect_b64 s[20:21], -1, 0
	v_writelane_b32 v249, s20, 19
	s_cmp_eq_u32 s48, 3
	s_nop 0
	v_writelane_b32 v249, s21, 20
	s_cselect_b64 s[20:21], -1, 0
	v_writelane_b32 v249, s20, 21
	s_cmp_eq_u32 s48, 2
	s_nop 0
	v_writelane_b32 v249, s21, 22
	s_cselect_b64 s[20:21], -1, 0
	v_writelane_b32 v249, s20, 23
	s_cmp_eq_u32 s48, 1
	s_nop 0
	v_writelane_b32 v249, s21, 24
	s_cselect_b64 s[20:21], -1, 0
	v_writelane_b32 v249, s20, 25
	s_cmp_eq_u32 s48, 0
	s_nop 0
	v_writelane_b32 v249, s21, 26
	s_cselect_b64 s[20:21], -1, 0
	s_lshl_b32 s18, s48, 8
	s_add_u32 s0, s0, s18
	v_writelane_b32 v249, s20, 27
	s_addc_u32 s1, s1, 0
	s_nop 0
	v_writelane_b32 v249, s21, 28
	s_add_u32 s20, s0, 0x1400
	s_addc_u32 s21, s1, 0
	v_writelane_b32 v249, s20, 29
	s_add_u32 s0, s0, 0x2400
	s_addc_u32 s1, s1, 0
	v_writelane_b32 v249, s21, 30
	v_writelane_b32 v249, s0, 31
	s_nop 1
	v_writelane_b32 v249, s1, 32
	s_add_u32 s0, s70, 0x7400
	s_addc_u32 s1, s71, 0
	v_writelane_b32 v249, s0, 33
	s_nop 1
	v_writelane_b32 v249, s1, 34
	s_add_u32 s0, s70, 0x7500
	s_addc_u32 s1, s71, 0
	v_writelane_b32 v249, s0, 35
	s_nop 1
	v_writelane_b32 v249, s1, 36
	s_add_u32 s0, s70, 0x55f00000
	v_writelane_b32 v249, s0, 37
	s_addc_u32 s0, s71, 0
	v_writelane_b32 v249, s0, 38
	s_add_u32 s0, s70, 0x58300000
	v_writelane_b32 v249, s0, 39
	s_addc_u32 s0, s71, 0
	v_writelane_b32 v249, s0, 40
	s_add_u32 s0, s70, 0x5cb00000
	s_addc_u32 s1, s71, 0
	s_add_u32 s42, s70, 0x5ef00000
	s_addc_u32 s43, s71, 0
	s_add_u32 s44, s70, 0x5f300000
	v_writelane_b32 v249, s0, 41
	s_addc_u32 s45, s71, 0
	s_nop 0
	v_writelane_b32 v249, s1, 42
	s_add_u32 s0, s70, 0x64d00000
	v_writelane_b32 v249, s0, 43
	s_addc_u32 s0, s71, 0
	v_writelane_b32 v249, s0, 44
	s_add_u32 s0, s70, 0x65f00000
	v_writelane_b32 v249, s0, 45
	s_addc_u32 s0, s71, 0
	s_add_u32 s48, s70, 0x68300000
	s_addc_u32 s49, s71, 0
	s_add_u32 s50, s70, 0x69500000
	s_addc_u32 s51, s71, 0
	v_writelane_b32 v249, s0, 46
	s_add_u32 s0, s70, 0x69600000
	s_addc_u32 s1, s71, 0
	s_add_u32 s52, s70, 0x69700000
	v_writelane_b32 v249, s0, 47
	s_addc_u32 s53, s71, 0
	s_nop 0
	v_writelane_b32 v249, s1, 48
	s_add_u32 s0, s70, 0x1200000
	v_writelane_b32 v249, s0, 49
	s_addc_u32 s0, s71, 0
	v_writelane_b32 v249, s0, 50
	s_add_u32 s0, s70, 0x1208000
	s_addc_u32 s1, s71, 0
	v_writelane_b32 v249, s0, 51
	s_nop 1
	v_writelane_b32 v249, s1, 52
	s_add_u32 s0, s70, 0x1209000
	s_addc_u32 s1, s71, 0
	v_writelane_b32 v249, s0, 53
	s_lshl_b32 s41, s46, 8
	s_lshl_b32 s54, s30, 3
	v_writelane_b32 v249, s1, 54
	s_lshl_b32 s0, s46, 11
	v_writelane_b32 v249, s0, 55
	s_add_i32 s0, s0, 0
	s_add_i32 s0, s0, 0x12000
	v_writelane_b32 v249, s0, 56
	v_writelane_b32 v249, s19, 57
	s_sub_i32 s0, s19, s41
	v_writelane_b32 v249, s0, 58
	s_lshl_b32 s0, s46, 10
	s_cmp_eq_u32 s46, 4
	v_writelane_b32 v249, s0, 59
	s_cselect_b64 s[0:1], -1, 0
	s_and_b64 s[0:1], s[0:1], s[2:3]
	s_add_i32 s3, s47, 0x400
	s_add_i32 s2, s47, s41
	s_add_u32 s18, s70, 0x60500000
	s_addc_u32 s19, s71, 0
	v_writelane_b32 v249, s18, 60
	s_nop 1
	v_writelane_b32 v249, s19, 61
	s_add_u32 s18, s70, 0x6a900000
	s_addc_u32 s19, s71, 0
	v_writelane_b32 v249, s18, 62
	s_cmpk_gt_i32 s34, 0x1ff
	s_nop 0
	v_writelane_b32 v249, s19, 63
	s_cselect_b64 s[18:19], -1, 0
	v_writelane_b32 v250, s18, 0
	s_cmpk_lt_u32 s34, 0x300
	s_nop 0
	v_writelane_b32 v250, s19, 1
	s_cselect_b64 s[18:19], -1, 0
	s_add_i32 s22, s34, 0xfffffe00
	s_lshr_b32 s23, s22, 6
	v_writelane_b32 v250, s18, 2
	s_bfe_i32 s26, s33, 0x10008
	s_lshl_b32 s27, s23, 2
	v_writelane_b32 v250, s19, 3
	s_add_i32 s28, s27, 0x80
	s_and_b32 s18, s26, 3
	s_or_b32 s76, s28, s18
	s_add_i32 s18, s76, s55
	s_mov_b32 s19, s77
	s_bfe_u32 s60, s34, 0x30003
	s_lshl_b64 s[20:21], s[18:19], 3
	s_or_b32 s20, s20, s60
	s_bfe_u32 s19, s33, 0x10007
	s_lshl_b32 s24, s19, 5
	s_lshl_b64 s[56:57], s[20:21], 9
	s_lshl_b32 s22, s22, 6
	v_writelane_b32 v250, s24, 4
	s_or_b32 s56, s56, s24
	s_and_b32 s22, s22, 64
	s_lshl_b64 s[24:25], s[76:77], 13
	v_writelane_b32 v250, s56, 5
	s_or_b32 s24, s24, s22
	s_lshl_b64 s[20:21], s[20:21], 8
	v_writelane_b32 v250, s57, 6
	s_add_u32 s20, s50, s20
	v_writelane_b32 v250, s22, 7
	s_addc_u32 s21, s51, s21
	s_lshl_b32 s29, s19, 7
	v_writelane_b32 v250, s24, 8
	s_add_u32 s20, s20, s29
	s_addc_u32 s21, s21, 0
	v_writelane_b32 v250, s25, 9
	v_writelane_b32 v250, s20, 10
	s_lshl_b32 s59, s23, 5
	s_lshl_b32 s19, s19, 9
	v_writelane_b32 v250, s21, 11
	s_or_b32 s20, s16, s28
	s_add_i32 s76, s20, 1
	s_add_i32 s20, s76, s55
	s_mov_b32 s21, s77
	s_lshl_b64 s[22:23], s[20:21], 3
	s_lshl_b32 s56, s60, 10
	s_or_b32 s22, s22, s60
	s_or_b32 s57, s56, s19
	s_lshl_b64 s[24:25], s[22:23], 13
	s_add_u32 s24, s48, s24
	s_addc_u32 s25, s49, s25
	v_writelane_b32 v250, s24, 12
	s_lshl_b64 s[22:23], s[22:23], 8
	s_nop 0
	v_writelane_b32 v250, s25, 13
	s_lshl_b64 s[24:25], s[76:77], 13
	s_add_u32 s19, s50, s22
	s_addc_u32 s21, s51, s23
	v_writelane_b32 v250, s24, 14
	s_add_u32 s22, s19, s29
	s_addc_u32 s23, s21, 0
	v_writelane_b32 v250, s25, 15
; #define GAS __attribute__((address_space(1)))
; template <int DK> __device__ __forceinline__ void p2_load(P2Frag<DK>& f, const ScanBufs<DK>& S, int dir, int g, int h, int dkb, int dvb, int r, int hi) {
;     const bf16* kt = S.KT + (((((size_t)dir * NCH + g) * 8 + h) * 8 + hi) * DK + dkb * 32 + r) * 8;
;     const bf16* vt = S.VT + ((((size_t)g * 8 + h) * 8 + hi) * 128 + dvb * 64 + r) * 8;
;     const float* ae = S.AE + (((size_t)dir * NCH + g) * 8 + h) * DK + dkb * 32 + 4 * hi;
; #pragma unroll
;     for (int kk = 0; kk < 4; ++kk) { f.a[kk] = *(const GAS bf16x8*)(kt + (size_t)kk * 2 * DK * 8); f.bv[0][kk] = *(const GAS bf16x8*)(vt + (size_t)kk * 2 * 128 * 8); f.bv[1][kk] = *(const GAS bf16x8*)(vt + (size_t)kk * 2 * 128 * 8 + 32 * 8); f.ae[kk] = *(const GAS f32x4*)(ae + 8 * kk); }
; }
; template <int DK> __device__ __forceinline__ void scan_state_unit(const ScanBufs<DK>& S, int unit, int lane, bool skip_ctx_store) {
;     constexpr int NKB = DK / 32;
;     const int dvb = unit & 1, dkb = (unit >> 1) % NKB, rest = (unit >> 1) / NKB; const int dir = rest & 1, h = (rest >> 1) & 7, b = rest >> 4;
;     const int r = lane & 31, hi = lane >> 5;
;     f32x16 acc[2]; acc[0] = f32x16{}; acc[1] = f32x16{};
;     P2Frag<DK> cur, nxt; p2_load<DK>(cur, S, dir, scan_chunk(b, dir, 0), h, dkb, dvb, r, hi);
;     for (int s = 0; s < 36; ++s) {
;         const int g = scan_chunk(b, dir, s);
;         if (s + 1 < 36) p2_load<DK>(nxt, S, dir, scan_chunk(b, dir, s + 1), h, dkb, dvb, r, hi);
;         if (!(skip_ctx_store && s < 4)) {
;             bf16* sp = S.SP + (((((size_t)dir * NCH + g) * 8 + h) * (DK / 8) + dkb * 4) * 128 + dvb * 64 + r) * 8 + 4 * hi;
	v_writelane_b32 v250, s22, 16
	s_lshl_b32 s18, s18, 13
	s_sub_i32 s19, s27, s16
	v_writelane_b32 v250, s23, 17
	s_add_i32 s76, s19, 0x82
	s_or_b32 s18, s18, s57
	v_writelane_b32 v250, s18, 18
	s_add_i32 s18, s76, s55
	s_mov_b32 s19, s77
	s_lshl_b64 s[18:19], s[18:19], 3
	s_or_b32 s18, s18, s60
	s_lshl_b64 s[22:23], s[18:19], 13
	s_add_u32 s22, s48, s22
	s_addc_u32 s23, s49, s23
	v_writelane_b32 v250, s22, 19
	s_lshl_b64 s[18:19], s[18:19], 8
	s_mulk_i32 s16, 0x8f
	v_writelane_b32 v250, s23, 20
	s_lshl_b64 s[22:23], s[76:77], 13
	s_add_u32 s18, s50, s18
	s_addc_u32 s19, s51, s19
	v_writelane_b32 v250, s22, 21
	s_add_u32 s18, s18, s29
	s_addc_u32 s19, s19, 0
	v_writelane_b32 v250, s23, 22
	v_writelane_b32 v250, s18, 23
	s_or_b32 s76, s28, s17
	s_nop 0
	v_writelane_b32 v250, s19, 24
	s_lshl_b32 s18, s20, 13
	s_or_b32 s17, s18, s57
	s_add_i32 s18, s76, s55
	s_mov_b32 s19, s77
	s_lshl_b64 s[20:21], s[18:19], 3
	s_or_b32 s20, s20, s60
	v_writelane_b32 v250, s17, 25
	s_lshl_b64 s[22:23], s[20:21], 13
	s_add_u32 s22, s48, s22
	v_writelane_b32 v250, s48, 26
	s_addc_u32 s23, s49, s23
	s_lshl_b64 s[20:21], s[20:21], 8
	v_writelane_b32 v250, s49, 27
	v_writelane_b32 v250, s22, 28
	s_mov_b32 s49, s77
	s_nop 0
	v_writelane_b32 v250, s23, 29
	s_lshl_b64 s[22:23], s[76:77], 13
	s_add_u32 s17, s50, s20
	v_writelane_b32 v250, s22, 30
	s_addc_u32 s20, s51, s21
	s_nop 0
	v_writelane_b32 v250, s23, 31
	s_add_u32 s22, s17, s29
	s_addc_u32 s23, s20, 0
	s_add_i32 s16, s16, s28
	s_lshl_b32 s16, s16, 13
	v_writelane_b32 v250, s22, 32
	s_or_b32 s16, s16, s57
	s_addk_i32 s16, 0x4000
	v_writelane_b32 v250, s23, 33
	v_writelane_b32 v250, s16, 34
	s_add_u32 s16, s50, s29
	v_writelane_b32 v250, s50, 35
	s_addc_u32 s17, s51, 0
	s_nop 0
	v_writelane_b32 v250, s51, 36
	v_writelane_b32 v250, s16, 37
	s_nop 1
	v_writelane_b32 v250, s17, 38
	s_and_b32 s16, s26, 31
	s_or_b32 s76, s59, s16
	s_add_i32 s16, s76, s55
	s_mov_b32 s17, s77
	s_lshl_b64 s[16:17], s[16:17], 3
	s_or_b32 s16, s16, s60
	s_lshl_b64 s[20:21], s[16:17], 13
	v_writelane_b32 v250, s20, 39
	s_nop 1
	v_writelane_b32 v250, s21, 40
	s_lshl_b64 s[20:21], s[76:77], 17
	s_add_u32 s20, s52, s20
	v_writelane_b32 v250, s52, 41
	s_addc_u32 s21, s53, s21
	s_lshl_b64 s[16:17], s[16:17], 8
	v_writelane_b32 v250, s53, 42
	v_writelane_b32 v250, s20, 43
	s_ashr_i32 s23, s14, 6
	s_bfe_i32 s26, s13, 0x10000
	v_writelane_b32 v250, s21, 44
	v_writelane_b32 v250, s16, 45
	s_lshl_b32 s27, s23, 2
	s_and_b32 s20, s14, -4
	v_writelane_b32 v250, s17, 46
	s_lshl_b64 s[16:17], s[18:19], 13
	s_add_i32 s28, s27, 0x80
	s_and_b32 s14, s26, 3
	s_or_b32 s16, s16, s57
	s_or_b32 s14, s28, s14
	s_sub_i32 s22, s15, s20
	v_writelane_b32 v250, s16, 47
	s_ashr_i32 s15, s14, 31
	s_bfe_u32 s64, s13, 0x30001
	v_writelane_b32 v250, s17, 48
	s_add_u32 s16, s14, s62
	s_addc_u32 s17, s15, 0
	s_lshl_b64 s[18:19], s[16:17], 3
	s_or_b32 s18, s18, s64
	s_lshl_b32 s24, s22, 5
	s_ashr_i32 s25, s24, 31
	s_lshl_b64 s[20:21], s[18:19], 10
	s_add_u32 s13, s20, s24
	v_writelane_b32 v250, s13, 49
	s_addc_u32 s13, s21, s25
	s_lshl_b64 s[14:15], s[14:15], 13
	s_and_b32 s29, s33, 64
	v_writelane_b32 v250, s13, 50
	s_or_b32 s14, s14, s29
	v_writelane_b32 v250, s14, 51
	s_lshl_b32 s48, s64, 10
	s_nop 0
	v_writelane_b32 v250, s15, 52
	s_lshl_b64 s[14:15], s[18:19], 9
	s_add_u32 s13, s42, s14
	s_addc_u32 s18, s43, s15
	v_writelane_b32 v250, s24, 53
	s_lshl_b64 s[14:15], s[24:25], 2
	s_add_u32 s20, s13, s14
	s_addc_u32 s21, s18, s15
	s_lshl_b32 s13, s22, 2
	s_lshl_b32 s63, s23, 5
	s_lshl_b32 s18, s64, 4
	s_ashr_i32 s19, s13, 31
	v_writelane_b32 v250, s25, 54
	s_add_u32 s18, s18, s13
	v_writelane_b32 v250, s20, 55
	s_addc_u32 s19, 0, s19
	s_or_b32 s13, s12, s28
	v_writelane_b32 v250, s21, 56
	s_add_i32 s20, s13, 1
	s_ashr_i32 s21, s20, 31
	s_add_u32 s22, s20, s62
	s_addc_u32 s23, s21, 0
	s_lshl_b64 s[24:25], s[22:23], 3
	s_lshl_b64 s[20:21], s[20:21], 13
	s_or_b32 s24, s24, s64
	v_writelane_b32 v250, s20, 57
	s_nop 1
	v_writelane_b32 v250, s21, 58
	s_lshl_b64 s[20:21], s[24:25], 14
	v_writelane_b32 v250, s20, 59
	s_nop 1
	v_writelane_b32 v250, s21, 60
	s_lshl_b64 s[20:21], s[24:25], 9
	s_add_u32 s13, s42, s20
	s_addc_u32 s20, s43, s21
	s_add_u32 s50, s13, s14
	s_addc_u32 s51, s20, s15
	v_writelane_b32 v250, s50, 61
	s_lshl_b64 s[16:17], s[16:17], 14
	s_mov_b32 s25, s55
	v_writelane_b32 v250, s51, 62
	s_lshl_b64 s[50:51], s[18:19], 7
	s_add_u32 s13, s16, s50
	s_addc_u32 s16, s17, s51
	s_sub_i32 s12, s27, s12
	s_or_b32 s13, s13, s29
	s_addk_i32 s12, 0x82
	v_writelane_b32 v251, s13, 0
	s_ashr_i32 s13, s12, 31
	v_writelane_b32 v250, s16, 63
	s_add_u32 s16, s12, s62
	s_addc_u32 s17, s13, 0
	s_lshl_b64 s[18:19], s[16:17], 3
	s_lshl_b64 s[12:13], s[12:13], 13
	s_or_b32 s18, s18, s64
	v_writelane_b32 v251, s12, 1
	s_nop 1
	v_writelane_b32 v251, s13, 2
	s_lshl_b64 s[12:13], s[18:19], 14
	v_writelane_b32 v251, s12, 3
	s_nop 1
	v_writelane_b32 v251, s13, 4
	s_lshl_b64 s[12:13], s[18:19], 9
	s_add_u32 s12, s42, s12
	s_addc_u32 s13, s43, s13
	s_add_u32 s12, s12, s14
	s_addc_u32 s13, s13, s15
	v_writelane_b32 v251, s12, 5
	s_nop 1
	v_writelane_b32 v251, s13, 6
	s_lshl_b64 s[12:13], s[22:23], 14
	s_add_u32 s12, s12, s50
	s_addc_u32 s13, s13, s51
	v_writelane_b32 v251, s13, 7
	s_or_b32 s12, s12, s29
	v_writelane_b32 v251, s12, 8
	s_or_b32 s12, s11, s28
	s_ashr_i32 s13, s12, 31
	s_add_u32 s18, s12, s62
	s_addc_u32 s19, s13, 0
	s_lshl_b64 s[20:21], s[18:19], 3
	s_lshl_b64 s[12:13], s[12:13], 13
	s_or_b32 s20, s20, s64
	v_writelane_b32 v251, s12, 9
	s_nop 1
	v_writelane_b32 v251, s13, 10
	s_lshl_b64 s[12:13], s[20:21], 14
	v_writelane_b32 v251, s12, 11
	s_nop 1
	v_writelane_b32 v251, s13, 12
;     __host__ __device__ bool next(int i, Unit& u) const { return tile((long)i * G + c, u); }
;     __host__ __device__ bool next(int i, Unit& u) const { if (!tile((long)(i / NZ) * G + c, u)) return false; u.z = i % NZ; return true; }
;     __host__ __device__ bool next(int i, Unit& u) const { const long L = (long)i * G + c; if (L >= nwg) return false; const int t = (int)L / (NS * NZ), rem = (int)L % (NS * NZ), z = rem / NS, ks = rem % NS;
;         u.pm = pm0 + t / nN; u.pn = t % nN; u.z = z; u.k0 = ks * Kc; u.zo = z * NS + ks; return true; }
; __device__ __forceinline__ void convert_pocket(Frame& F, int lnext, int r_lo, int r_hi, int first_idle) {
;     const int c = (int)blockIdx.x; if (lnext >= DEPTH || c < first_idle) return;
;     convert_items(F, lnext, r_lo, r_hi, (c - first_idle) * NWAVES + F.wave, ((int)gridDim.x - first_idle) * NWAVES);
; }
	s_lshl_b64 s[12:13], s[20:21], 9
	s_add_u32 s11, s42, s12
	s_addc_u32 s12, s43, s13
	s_add_u32 s20, s11, s14
	s_addc_u32 s21, s12, s15
	s_lshl_b64 s[12:13], s[16:17], 14
	v_writelane_b32 v251, s20, 13
	s_add_u32 s11, s12, s50
	s_addc_u32 s12, s13, s51
	v_writelane_b32 v251, s21, 14
	v_writelane_b32 v251, s12, 15
	s_or_b32 s11, s11, s29
	v_writelane_b32 v251, s11, 16
	s_add_u32 s12, s42, s14
	v_writelane_b32 v251, s42, 17
	s_addc_u32 s13, s43, s15
	s_and_b32 s11, s26, 31
	v_writelane_b32 v251, s43, 18
	v_writelane_b32 v251, s12, 19
	s_mov_b64 s[26:27], s[36:37]
	s_nop 0
	v_writelane_b32 v251, s13, 20
	s_or_b32 s12, s11, s63
	s_ashr_i32 s13, s12, 31
	s_add_u32 s14, s12, s62
	s_addc_u32 s15, s13, 0
	s_lshl_b64 s[14:15], s[14:15], 3
	s_or_b32 s14, s14, s64
	s_lshl_b64 s[16:17], s[14:15], 14
	v_writelane_b32 v251, s16, 21
	s_lshl_b64 s[12:13], s[12:13], 17
	s_add_u32 s12, s44, s12
	v_writelane_b32 v251, s17, 22
	v_writelane_b32 v251, s44, 23
	s_addc_u32 s13, s45, s13
	s_mul_i32 s11, s46, 0x4800
	v_writelane_b32 v251, s45, 24
	v_writelane_b32 v251, s12, 25
	s_nop 1
	v_writelane_b32 v251, s13, 26
	s_lshl_b64 s[12:13], s[14:15], 9
	v_writelane_b32 v251, s12, 27
	s_nop 1
	v_writelane_b32 v251, s13, 28
	s_lshl_b64 s[12:13], s[18:19], 18
	v_writelane_b32 v251, s12, 29
	s_nop 1
	v_writelane_b32 v251, s13, 30
	s_add_u32 s12, s70, 0x43f00000
	v_writelane_b32 v251, s12, 31
	s_addc_u32 s12, s71, 0
	v_writelane_b32 v251, s12, 32
	s_add_u32 s12, s70, 0x10000
	v_writelane_b32 v251, s12, 33
	s_addc_u32 s12, s71, 0
	v_writelane_b32 v251, s12, 34
	s_add_u32 s12, s70, 0x2e404800
	v_writelane_b32 v251, s12, 35
	s_addc_u32 s12, s71, 0
	v_writelane_b32 v251, s12, 36
	s_add_u32 s12, s70, 0x2e405000
	v_writelane_b32 v251, s12, 37
	s_addc_u32 s12, s71, 0
	s_add_u32 s18, s70, 0x41b00000
	v_writelane_b32 v251, s12, 38
	s_addc_u32 s19, s71, 0
	s_add_i32 s11, s11, 0
	v_writelane_b32 v251, s11, 39
	s_mul_i32 s11, s30, s46
	s_add_i32 s11, s47, s11
	s_cmp_eq_u32 s46, 5
	v_writelane_b32 v251, s11, 40
	s_cselect_b64 s[12:13], -1, 0
	v_writelane_b32 v251, s12, 41
	s_add_i32 s11, s47, s54
	s_nop 0
	v_writelane_b32 v251, s13, 42
	v_writelane_b32 v251, s11, 43
	s_add_u32 s11, s70, 0x42d00000
	v_writelane_b32 v251, s11, 44
	s_addc_u32 s11, s71, 0
	s_add_u32 s20, s70, 0x45100000
	s_addc_u32 s21, s71, 0
	s_add_u32 s12, s70, 0x2e405800
	v_writelane_b32 v251, s11, 45
	s_addc_u32 s13, s71, 0
	v_writelane_b32 v251, s12, 46
	s_cmpk_lt_i32 s81, 0x100
	s_nop 0
	v_writelane_b32 v251, s13, 47
	s_cselect_b64 s[12:13], -1, 0
	s_lshl_b32 s11, s40, 5
	s_add_u32 s22, s70, 0x71d00000
	s_addc_u32 s23, s71, 0
	v_writelane_b32 v251, s12, 48
	s_cmpk_lt_i32 s81, 0x60
	s_nop 0
	v_writelane_b32 v251, s13, 49
	s_cselect_b64 s[12:13], -1, 0
	v_writelane_b32 v251, s12, 50
	s_cmpk_gt_i32 s81, 0x5f
	s_cselect_b64 s[14:15], -1, 0
	v_writelane_b32 v251, s13, 51
	s_mul_hi_i32 s12, s81, 0x55555556
	s_lshr_b32 s13, s12, 31
	v_writelane_b32 v251, s14, 52
	s_add_i32 s12, s12, s13
	s_ashr_i32 s16, s12, 31
	v_writelane_b32 v251, s15, 53
	s_mul_hi_i32 s14, s81, 0x2aaaaaab
	s_ashr_i32 s13, s14, 2
	s_lshr_b32 s15, s14, 31
	s_lshr_b32 s16, s16, 29
	s_add_i32 s13, s13, s15
	s_add_i32 s16, s12, s16
	s_and_b32 s16, s16, -8
	s_mul_i32 s17, s12, 3
	s_add_i32 s44, s13, 32
	s_sub_i32 s36, s12, s16
	s_sub_i32 s42, s81, s17
	s_mov_b32 s12, s44
	s_ashr_i32 s43, s42, 31
	s_ashr_i32 s45, s44, 31
	s_ashr_i32 s37, s36, 31
	v_writelane_b32 v251, s12, 54
	s_mul_i32 s16, s42, 0x1200000
	s_mov_b32 s24, s36
	v_writelane_b32 v251, s13, 55
	s_lshl_b64 s[12:13], s[44:45], 19
	s_lshl_b64 s[44:45], s[42:43], 22
	s_lshl_b64 s[36:37], s[36:37], 19
	s_add_u32 s16, s18, s16
	s_mul_hi_i32 s17, s42, 0x1200000
	s_addc_u32 s17, s19, s17
	s_add_u32 s12, s16, s12
	s_addc_u32 s13, s17, s13
	s_add_u32 s16, s12, 0x40000
	v_writelane_b32 v247, s12, 0
	s_addc_u32 s17, s13, 0
	s_cmpk_lg_i32 s30, 0x100
	v_writelane_b32 v247, s13, 1
	v_writelane_b32 v247, s16, 2
	s_cselect_b64 s[12:13], -1, 0
	v_writelane_b32 v251, s44, 56
	v_writelane_b32 v247, s17, 3
	v_writelane_b32 v247, s12, 4
	v_writelane_b32 v251, s45, 57
	v_writelane_b32 v251, s24, 58
	v_writelane_b32 v247, s13, 5
	s_add_i32 s12, s9, 0x3ee4
	s_cmpk_lt_i32 s12, 0x6e6c
	v_writelane_b32 v247, s12, 6
	s_cselect_b64 s[12:13], -1, 0
	v_writelane_b32 v247, s12, 7
	v_writelane_b32 v251, s25, 59
	v_writelane_b32 v251, s36, 60
	v_writelane_b32 v247, s13, 8
	s_add_u32 s12, s70, 0x17800000
	v_writelane_b32 v247, s12, 9
	s_addc_u32 s12, s71, 0
	v_writelane_b32 v247, s12, 10
	s_add_u32 s12, s70, 0x15800000
	v_writelane_b32 v247, s12, 11
	s_addc_u32 s12, s71, 0
	v_writelane_b32 v251, s37, 61
	s_add_u32 s36, s70, 0x47500000
	s_addc_u32 s37, s71, 0
	v_writelane_b32 v247, s12, 12
	s_add_u32 s12, s70, 0x6bd00000
	v_writelane_b32 v247, s12, 13
	s_addc_u32 s12, s71, 0
	s_cmpk_lt_i32 s81, 0xc0
	v_writelane_b32 v247, s12, 14
	s_cselect_b64 s[12:13], -1, 0
	v_writelane_b32 v247, s12, 15
	s_mov_b32 s24, s42
	v_writelane_b32 v251, s24, 62
	v_writelane_b32 v247, s13, 16
	s_add_i32 s12, s14, s15
	s_mul_i32 s13, s12, 6
	s_sub_i32 s13, s81, s13
	s_bfe_u32 s16, s13, 0x10007
	s_add_i32 s16, s13, s16
	s_and_b32 s17, s16, 0xfe
	s_sub_i32 s13, s13, s17
	s_ashr_i32 s14, s14, 3
	s_add_i32 s17, s14, s15
	s_sext_i32_i8 s15, s13
	s_ashr_i32 s13, s12, 31
	s_lshr_b32 s13, s13, 29
	s_bfe_i32 s14, s16, 0x80000
	s_add_i32 s13, s12, s13
	s_sext_i32_i16 s14, s14
	s_and_b32 s13, s13, -8
	s_sub_i32 s16, s12, s13
	s_and_b32 s12, s14, -2
	s_add_i32 s12, s12, s15
	v_writelane_b32 v247, s12, 17
	s_lshr_b32 s12, s14, 1
	s_lshl_b32 s14, s15, 10
	s_bfe_i64 s[12:13], s[12:13], 0x100000
	s_ashr_i32 s15, s14, 31
	s_lshl_b64 s[12:13], s[12:13], 22
;     __host__ __device__ bool next(int i, Unit& u) const { return tile((long)i * G + c, u); }
;     __host__ __device__ bool next(int i, Unit& u) const { if (!tile((long)(i / NZ) * G + c, u)) return false; u.z = i % NZ; return true; }
;     __host__ __device__ bool next(int i, Unit& u) const { const long L = (long)i * G + c; if (L >= nwg) return false; const int t = (int)L / (NS * NZ), rem = (int)L % (NS * NZ), z = rem / NS, ks = rem % NS;
;         u.pm = pm0 + t / nN; u.pn = t % nN; u.z = z; u.k0 = ks * Kc; u.zo = z * NS + ks; return true; }
; __device__ __forceinline__ void convert_pocket(Frame& F, int lnext, int r_lo, int r_hi, int first_idle) {
;     const int c = (int)blockIdx.x; if (lnext >= DEPTH || c < first_idle) return;
;     convert_items(F, lnext, r_lo, r_hi, (c - first_idle) * NWAVES + F.wave, ((int)gridDim.x - first_idle) * NWAVES);
; }
	s_lshl_b64 s[42:43], s[14:15], 1
	s_add_i32 s44, s17, 32
	v_writelane_b32 v247, s22, 18
	s_add_u32 s14, s22, s12
	v_writelane_b32 v247, s23, 19
	s_mov_b32 s12, s44
	s_addc_u32 s15, s23, s13
	s_ashr_i32 s45, s44, 31
	v_writelane_b32 v247, s12, 20
	v_writelane_b32 v251, s25, 63
	s_nop 0
	v_writelane_b32 v247, s13, 21
	s_lshl_b64 s[12:13], s[44:45], 20
	s_add_u32 s12, s14, s12
	s_mov_b32 s14, s16
	s_addc_u32 s13, s15, s13
	s_ashr_i32 s17, s16, 31
	v_writelane_b32 v247, s14, 22
	s_nop 1
	v_writelane_b32 v247, s15, 23
	s_lshl_b64 s[14:15], s[16:17], 20
	v_writelane_b32 v247, s14, 24
	s_add_u32 s12, s12, s42
	s_nop 0
	v_writelane_b32 v247, s15, 25
	v_writelane_b32 v247, s42, 26
	s_addc_u32 s13, s13, s43
	s_add_u32 s14, s12, 0x80000
	v_writelane_b32 v247, s43, 27
	v_writelane_b32 v247, s12, 28
	s_addc_u32 s15, s13, 0
	s_nop 0
	v_writelane_b32 v247, s13, 29
	v_writelane_b32 v247, s14, 30
	s_add_u32 s12, s70, 0x1100000
	s_nop 0
	v_writelane_b32 v247, s15, 31
	v_writelane_b32 v247, s12, 32
	s_addc_u32 s12, s71, 0
	s_add_u32 s16, s70, 0x27800000
	s_addc_u32 s17, s71, 0
	v_writelane_b32 v247, s12, 33
	s_add_u32 s12, s70, 0x1104000
	s_addc_u32 s13, s71, 0
	v_writelane_b32 v247, s12, 34
	s_add_u32 s22, s70, 0x6dd00000
	s_addc_u32 s23, s71, 0
	v_writelane_b32 v247, s13, 35
	s_add_i32 s12, s10, s46
	s_add_i32 s14, s12, 0x2000
	s_mov_b32 s10, s14
	s_ashr_i32 s15, s14, 31
	s_ashr_i32 s13, s12, 31
	v_writelane_b32 v247, s10, 36
	s_ashr_i32 s24, s47, 6
	s_lshl_b64 s[42:43], s[14:15], 13
	v_writelane_b32 v247, s11, 37
	s_lshl_b64 s[14:15], s[12:13], 12
	v_writelane_b32 v247, s22, 38
	s_add_u32 s10, s22, s14
	v_writelane_b32 v247, s10, 39
	v_writelane_b32 v247, s23, 40
	s_addc_u32 s10, s23, s15
	v_writelane_b32 v247, s10, 41
	s_mul_i32 s10, s47, 28
	s_add_i32 s12, s12, s10
	s_mov_b32 s10, s12
	s_ashr_i32 s13, s12, 31
	v_writelane_b32 v247, s10, 42
	s_lshl_b64 s[14:15], s[12:13], 13
	s_lshl_b64 s[12:13], s[12:13], 12
	v_writelane_b32 v247, s11, 43
	s_add_u32 s12, s36, s12
	v_writelane_b32 v247, s36, 44
	s_addc_u32 s13, s37, s13
	s_ashr_i32 s10, s24, 31
	v_writelane_b32 v247, s37, 45
	v_writelane_b32 v247, s12, 46
	s_add_u32 s22, s70, 0x4bd00000
	s_addc_u32 s23, s71, 0
	v_writelane_b32 v247, s13, 47
	v_writelane_b32 v247, s24, 48
	s_cmpk_gt_i32 s81, 0x7f
	v_writelane_b32 v247, s10, 49
	s_cselect_b64 s[12:13], -1, 0
	v_writelane_b32 v247, s12, 50
	s_addk_i32 s9, 0x6a6c
	s_cmp_lt_i32 s9, 0x9900
	v_writelane_b32 v247, s13, 51
	v_writelane_b32 v247, s9, 52
	s_cselect_b64 s[12:13], -1, 0
	v_writelane_b32 v247, s12, 53
	s_add_u32 s9, s70, 0x1f800000
	s_nop 0
	v_writelane_b32 v247, s13, 54
	v_writelane_b32 v247, s9, 55
	s_addc_u32 s9, s71, 0
	v_writelane_b32 v247, s9, 56
	s_lshr_b32 s9, s31, 26
	s_add_i32 s9, s81, s9
	s_lshr_b32 s10, s35, 29
	s_lshl_b32 s12, s40, 10
	s_ashr_i32 s9, s9, 6
	s_add_i32 s10, s35, s10
	s_ashr_i32 s13, s12, 31
	v_writelane_b32 v247, s31, 57
	s_and_b32 s10, s10, -8
	s_lshl_b64 s[30:31], s[12:13], 1
	s_add_i32 s12, s9, 32
	s_ashr_i32 s13, s12, 31
	s_sub_i32 s36, s35, s10
	s_mov_b32 s10, s12
	v_writelane_b32 v247, s10, 58
	s_lshl_b64 s[12:13], s[12:13], 22
	s_add_u32 s9, s22, s12
	v_writelane_b32 v247, s11, 59
	s_mov_b32 s12, s36
	s_addc_u32 s10, s23, s13
	s_ashr_i32 s37, s36, 31
	v_writelane_b32 v247, s12, 60
	s_nop 1
	v_writelane_b32 v247, s13, 61
	s_lshl_b64 s[12:13], s[36:37], 22
	v_writelane_b32 v247, s12, 62
	s_mov_b64 s[36:37], 0x80
	s_nop 0
	v_writelane_b32 v247, s13, 63
	s_add_u32 s12, s9, s30
	v_writelane_b32 v246, s30, 0
	s_addc_u32 s13, s10, s31
	s_mul_i32 s9, s40, 0x137
	v_writelane_b32 v246, s31, 1
	s_add_u32 s30, s12, 0x200000
	v_writelane_b32 v246, s12, 2
	s_addc_u32 s31, s13, 0
	s_nop 0
	v_writelane_b32 v246, s13, 3
	v_writelane_b32 v246, s30, 4
	s_add_u32 s12, s70, 0x110a000
	s_addc_u32 s13, s71, 0
	v_writelane_b32 v246, s31, 5
	v_writelane_b32 v246, s12, 6
	s_nop 1
	v_writelane_b32 v246, s13, 7
	s_add_u32 s12, s16, s42
	v_writelane_b32 v246, s42, 8
	s_addc_u32 s13, s17, s43
	s_nop 0
	v_writelane_b32 v246, s43, 9
	v_writelane_b32 v246, s12, 10
	s_nop 1
	v_writelane_b32 v246, s13, 11
	s_add_u32 s12, s16, s14
	v_writelane_b32 v246, s16, 12
	s_nop 1
	v_writelane_b32 v246, s17, 13
	v_writelane_b32 v246, s14, 14
	s_addc_u32 s13, s17, s15
	s_cmp_lt_i32 s40, 4
	s_cselect_b32 s8, s9, s8
	s_add_i32 s8, s8, s35
	s_mul_hi_i32 s9, s8, 0x76b981db
	s_lshr_b32 s10, s9, 31
	s_ashr_i32 s9, s9, 7
	s_add_i32 s9, s9, s10
	s_mul_i32 s10, s9, 0x114
	s_add_i32 s5, s5, s46
	s_lshl_b32 s9, s9, 2
	s_add_i32 s5, s5, s7
	s_sub_i32 s7, 36, s9
	v_writelane_b32 v246, s15, 15
	s_sub_i32 s8, s8, s10
	s_min_u32 s10, s7, 4
	s_add_i32 s7, s5, 0x480
	v_writelane_b32 v246, s12, 16
	s_cmpk_lt_i32 s5, 0x240
	v_cvt_f32_ubyte0_e32 v1, s10
	v_writelane_b32 v246, s13, 17
	s_cselect_b32 s12, s7, -1
	s_or_b32 s5, s6, s59
	s_add_i32 s76, s5, s25
	s_lshl_b64 s[6:7], s[76:77], 13
	v_writelane_b32 v246, s57, 18
	s_or_b32 s6, s6, s57
	v_writelane_b32 v246, s6, 19
	s_or_b32 s4, s4, s63
	s_or_b32 s50, s50, s29
	v_writelane_b32 v246, s7, 20
	s_ashr_i32 s5, s4, 31
	v_writelane_b32 v246, s29, 21
	s_add_u32 s4, s4, s62
	v_writelane_b32 v246, s50, 22
	s_addc_u32 s5, s5, 0
	s_lshl_b64 s[4:5], s[4:5], 18
	v_writelane_b32 v246, s51, 23
	v_writelane_b32 v246, s4, 24
	s_cmp_lt_i32 s40, 0
	v_cvt_f32_i32_e32 v0, s8
	v_writelane_b32 v246, s5, 25
	s_cselect_b64 s[4:5], -1, 0
	v_writelane_b32 v246, s4, 26
	v_rcp_iflag_f32_e32 v2, v1
	s_mov_b32 s57, s77
	v_writelane_b32 v246, s5, 27
	s_and_b64 s[4:5], s[4:5], exec
	s_mul_i32 s4, s40, 33
	s_cselect_b32 s4, s4, s11
	s_add_i32 s11, s4, s35
;     __host__ __device__ bool tile(long L, Unit& u) const {
;     ...
;         int wgid = (int)L; { const int q = nwg / NXCD, r = nwg % NXCD, xcd = wgid % NXCD, off = wgid / NXCD; wgid = (xcd < r ? xcd * (q + 1) : r * (q + 1) + (xcd - r) * q) + off; }
;         const int nig = wgm * nN, gid = wgid / nig, fm = gid * wgm, gsz = (nM - fm) < wgm ? (nM - fm) : wgm;
;         u.pm = fm + ((wgid % nig) % gsz); u.pn = (wgid % nig) / gsz; u.z = 0; u.k0 = 0; u.zo = 0; return true;
	s_ashr_i32 s13, s11, 31
	s_lshr_b32 s4, s13, 27
	s_add_i32 s4, s11, s4
	s_and_b32 s5, s4, 0xffe0
	s_sub_i32 s5, s11, s5
	s_bfe_i32 s6, s5, 0x80000
	s_bfe_u32 s6, s6, 0x2000d
	s_add_i32 s6, s5, s6
	s_and_b32 s7, s6, 0xfc
	s_sub_i32 s5, s5, s7
	s_ashr_i32 s4, s4, 5
	s_bfe_i32 s6, s6, 0x80000
	v_writelane_b32 v246, s40, 28
	s_lshl_b32 s4, s4, 2
	s_sext_i32_i16 s6, s6
	s_sext_i32_i8 s5, s5
	v_writelane_b32 v246, s35, 29
	s_add_i32 s14, s4, s5
	s_ashr_i32 s4, s6, 2
	v_writelane_b32 v246, s4, 30
	s_lshr_b32 s4, s6, 2
	s_bfe_i64 s[4:5], s[4:5], 0x100000
	s_lshl_b64 s[16:17], s[4:5], 20
	s_ashr_i32 s15, s14, 31
	v_writelane_b32 v246, s16, 31
	s_lshl_b64 s[6:7], s[14:15], 20
	s_add_u32 s6, s20, s6
	v_writelane_b32 v246, s17, 32
	v_writelane_b32 v246, s20, 33
	s_addc_u32 s7, s21, s7
	s_add_u32 s16, s6, 0x80000
	v_writelane_b32 v246, s21, 34
	v_writelane_b32 v246, s6, 35
	s_addc_u32 s17, s7, 0
	v_mul_f32_e32 v2, v0, v2
	v_writelane_b32 v246, s7, 36
	s_lshr_b32 s6, s13, 28
	s_add_i32 s6, s11, s6
	s_and_b32 s7, s6, 0xfff0
	s_sub_i32 s7, s11, s7
	s_bfe_u32 s11, s7, 0x10007
	s_add_i32 s11, s7, s11
	s_and_b32 s13, s11, 0xfe
	s_sub_i32 s7, s7, s13
	s_ashr_i32 s6, s6, 4
	s_bfe_i32 s11, s11, 0x80000
	v_writelane_b32 v246, s16, 37
	s_lshl_b32 s6, s6, 1
	s_sext_i32_i16 s11, s11
	s_sext_i32_i8 s7, s7
	v_writelane_b32 v246, s17, 38
	s_add_i32 s16, s6, s7
	s_ashr_i32 s6, s11, 1
	v_writelane_b32 v246, s6, 39
	s_lshr_b32 s6, s11, 1
	s_bfe_i64 s[6:7], s[6:7], 0x100000
	s_lshl_b64 s[6:7], s[6:7], 22
	v_writelane_b32 v246, s6, 40
	s_ashr_i32 s17, s16, 31
	v_trunc_f32_e32 v2, v2
	v_writelane_b32 v246, s7, 41
	s_mov_b32 s6, s16
	v_writelane_b32 v246, s6, 42
	v_fma_f32 v0, -v2, v1, v0
	s_nop 0
	v_writelane_b32 v246, s7, 43
	s_lshl_b64 s[6:7], s[16:17], 22
	s_add_u32 s6, s22, s6
	v_writelane_b32 v246, s22, 44
	s_addc_u32 s7, s23, s7
	s_add_u32 s16, s6, 0x200000
	v_writelane_b32 v246, s23, 45
	v_writelane_b32 v246, s6, 46
	s_addc_u32 s17, s7, 0
	s_and_b64 s[0:1], s[0:1], exec
	s_cselect_b32 s3, s3, s12
	s_cmpk_lt_u32 s33, 0x100
	v_writelane_b32 v246, s7, 47
	s_cselect_b64 s[0:1], -1, 0
	v_writelane_b32 v246, s16, 48
	v_cndmask_b32_e64 v198, 0, 1, s[0:1]
	s_and_b64 s[0:1], s[0:1], exec
	v_writelane_b32 v246, s17, 49
	s_cselect_b32 s0, s2, s3
	v_writelane_b32 v246, s0, 50
	s_lshl_b64 s[0:1], s[4:5], 19
	v_writelane_b32 v246, s0, 51
	s_nop 1
	v_writelane_b32 v246, s1, 52
	s_mov_b32 s0, s14
	v_writelane_b32 v246, s0, 53
	s_nop 1
	v_writelane_b32 v246, s1, 54
	s_lshl_b64 s[0:1], s[14:15], 19
	v_writelane_b32 v246, s18, 55
	s_add_u32 s0, s18, s0
	v_writelane_b32 v246, s19, 56
	s_addc_u32 s1, s19, s1
	s_add_u32 s2, s0, 0x40000
	v_writelane_b32 v246, s0, 57
	s_addc_u32 s3, s1, 0
	s_nop 0
	v_writelane_b32 v246, s1, 58
	v_writelane_b32 v246, s2, 59
	s_ashr_i32 s0, s8, 30
	s_nop 0
	v_writelane_b32 v246, s3, 60
	s_or_b32 s2, s0, 1
	v_cmp_ge_f32_e64 s[0:1], |v0|, v1
	v_cvt_i32_f32_e32 v0, v2
	s_and_b64 s[0:1], s[0:1], exec
	s_cselect_b32 s0, s2, 0
	v_readfirstlane_b32 s1, v0
	s_add_i32 s0, s1, s0
	s_mul_i32 s1, s0, s10
	s_sub_i32 s1, s8, s1
	s_sext_i32_i16 s1, s1
	s_bfe_i64 s[2:3], s[0:1], 0x100000
	s_lshl_b64 s[2:3], s[2:3], 20
	s_add_i32 s4, s9, s1
	v_writelane_b32 v246, s2, 61
	s_ashr_i32 s5, s4, 31
	s_sext_i32_i16 s0, s0
	v_writelane_b32 v246, s3, 62
	s_mov_b32 s2, s4
	v_writelane_b32 v246, s2, 63
	v_mbcnt_lo_u32_b32 v0, -1, 0
	v_mbcnt_hi_u32_b32 v201, -1, v0
	v_writelane_b32 v245, s3, 0
	s_lshl_b64 s[2:3], s[4:5], 20
	s_add_u32 s2, s38, s2
	v_writelane_b32 v245, s38, 1
	s_addc_u32 s3, s39, s3
	s_nop 0
	v_writelane_b32 v245, s39, 2
	v_writelane_b32 v245, s0, 3
	v_writelane_b32 v245, s56, 4
	s_add_u32 s0, s2, 0x80000
	s_nop 0
	v_writelane_b32 v245, s57, 5
	v_writelane_b32 v245, s48, 6
	s_nop 1
	v_writelane_b32 v245, s49, 7
	v_writelane_b32 v245, s2, 8
	s_addc_u32 s1, s3, 0
	s_ashr_i32 s35, s34, 31
	v_writelane_b32 v245, s3, 9
	v_writelane_b32 v245, s0, 10
	s_ashr_i32 s55, s54, 31
	s_nop 0
	v_writelane_b32 v245, s1, 11
	s_add_i32 s0, s41, 0
	v_writelane_b32 v245, s41, 12
	s_add_i32 s0, s0, 0x10800
	v_writelane_b32 v245, s0, 13
	v_readfirstlane_b32 s0, v198
	s_nop 1
	v_writelane_b32 v245, s0, 14
	s_add_i32 s0, 0, 0x12600
	v_writelane_b32 v245, s0, 15
	v_cmp_eq_u32_e64 s[0:1], 0, v44
	s_nop 1
	v_writelane_b32 v245, s0, 16
	s_nop 1
	v_writelane_b32 v245, s1, 17
	s_lshl_b64 s[0:1], s[34:35], 12
	v_writelane_b32 v245, s0, 18
	s_nop 1
	v_writelane_b32 v245, s1, 19
	s_lshl_b64 s[0:1], s[54:55], 12
	v_writelane_b32 v245, s0, 20
	s_nop 1
	v_writelane_b32 v245, s1, 21
	v_writelane_b32 v245, s34, 22
	s_lshl_b64 s[0:1], s[34:35], 13
	s_nop 0
	v_writelane_b32 v245, s35, 23
	v_writelane_b32 v245, s0, 24
	s_mov_b64 s[34:35], 0x45000
	s_nop 0
	v_writelane_b32 v245, s1, 25
	v_writelane_b32 v245, s54, 26
	s_lshl_b64 s[0:1], s[54:55], 13
	s_nop 0
	v_writelane_b32 v245, s55, 27
	v_writelane_b32 v245, s0, 28
	s_nop 1
	v_writelane_b32 v245, s1, 29
	v_writelane_b32 v245, s81, 30
	v_writelane_b32 v245, s82, 31
	s_mov_b32 s0, s77
	s_nop 0
	v_writelane_b32 v245, s83, 32
	v_writelane_b32 v245, s68, 33
	s_nop 1
	v_writelane_b32 v245, s69, 34
	v_writelane_b32 v245, s70, 35
	v_writelane_b32 v245, s71, 36
	v_writelane_b32 v245, s26, 37
	s_nop 1
	v_writelane_b32 v245, s27, 38
	v_writelane_b32 v245, s78, 39
	s_nop 1
	v_writelane_b32 v245, s79, 40
	v_writelane_b32 v245, s25, 41
	v_writelane_b32 v245, s60, 42
	s_nop 1
	v_writelane_b32 v245, s61, 43
	v_writelane_b32 v245, s59, 44
	v_writelane_b32 v245, s62, 45
	v_writelane_b32 v245, s64, 46
	s_nop 1
	v_writelane_b32 v245, s65, 47
	v_writelane_b32 v245, s63, 48
	s_branch .LBB0_300

; #define FIN(k) (kin_launder(F.kin)[k])
; __device__ __forceinline__ void convert_items(Frame& F, int l, int r_lo, int r_hi, int widx, int nw) {
;     ...
;     for (int it = r_lo + widx; it < r_hi; it += nw) { int r = it;
;         if (r < CV_IIN) { const int nbk = NINP / 32, kb = r / nbk, nb = r % nbk; p0_transpose_item(FIN(6) + (size_t)l * 2048 * NIN, NIN, in_src_col(32 * nb), 64 * kb, (bf16*)(F.ws + WS_WIN) + (size_t)l * NINP * 2048, 2048, 32 * nb, scr, lane); continue; } r -= CV_IIN;
.LBB0_330:
	s_add_i32 s0, s8, 0x260
	s_addk_i32 s7, 0x4c00
	s_cmpk_lt_i32 s8, 0x3f84
	s_mov_b32 s8, s0
	s_cbranch_scc0 .LBB0_341

; #define FIN(k) (kin_launder(F.kin)[k])
; __device__ __forceinline__ void convert_items(Frame& F, int l, int r_lo, int r_hi, int widx, int nw) {
;     ...
;     for (int it = r_lo + widx; it < r_hi; it += nw) { int r = it;
;         if (r < CV_IIN) { const int nbk = NINP / 32, kb = r / nbk, nb = r % nbk; p0_transpose_item(FIN(6) + (size_t)l * 2048 * NIN, NIN, in_src_col(32 * nb), 64 * kb, (bf16*)(F.ws + WS_WIN) + (size_t)l * NINP * 2048, 2048, 32 * nb, scr, lane); continue; } r -= CV_IIN;
;         if (r < CV_IBR) { const int n = r / 1024, rr = r % 1024, kb = rr / 64, nb = rr % 64; p0_transpose_item(FIN(13) + (size_t)(l * 3 + n) * 1024 * 2048, 2048, 32 * nb, 64 * kb, (bf16*)(F.ws + WS_WBR) + (size_t)(l * 3 + n) * 2048 * 1024, 1024, 32 * nb, scr, lane); continue; } r -= CV_IBR;
.LBB0_1245:
	s_add_i32 s0, s12, 0x500
	s_add_i32 s11, s11, 0xa000
	s_cmpk_lt_i32 s12, 0x696c
	s_mov_b32 s12, s0
	s_cbranch_scc0 .LBB0_1264
